# weight-conversion phase: next tile's loads kept in flight across the LDS transpose and stores; prep: next-token row prefetch
# speedup vs baseline: 1.0404x; 1.0019x over previous
; __device__ __forceinline__ float bf_lo(unsigned v) { return __uint_as_float(v << 16); }
; __device__ __forceinline__ float bf_hi(unsigned v) { return __uint_as_float(v & 0xffff0000u); }
; __device__ __forceinline__ float rinv_of(float ss, float invn) { return rsqrtf(ss * invn + 1e-6f); }
; __device__ __forceinline__ void rope_cs(int pos, float inv, float& c, float& s) {
;     double rev = (double)pos * (double)inv * 0.15915494309189535; rev -= __builtin_rint(rev);
;     const float f = (float)rev; s = __builtin_amdgcn_sinf(f); c = __builtin_amdgcn_cosf(f);
; __device__ __forceinline__ void prep_phase(const int TID, const int BID, PP p) {
;     ...
;     for (int tok = wg; tok < T; tok += nw) {
;         const bf16_t* r = raw + (size_t)tok * NINP; const int pos = tok & 4095;
;         float cq[4], sq[4], ci[4], si[4];
;         { const int j = lane & 3, ji = lane & 1;
; #pragma unroll
;           for (int e = 0; e < 4; ++e) {
;               rope_cs(pos, exp2f(-(float)(4 * j + e) * (L2T / 16.0f)), cq[e], sq[e]);
;               rope_cs(pos, exp2f(-(float)(4 * ji + e) * (L2T / 8.0f)), ci[e], si[e]); } }
; #pragma unroll
;         for (int it = 0; it < 10; ++it) {
;             const int head = 2 * it + (lane >> 5), j = lane & 31;
;             const bool isq = head < 16;
;             const int col = isq ? head * 128 : 2048 + (head - 16) * 128;
;             const u32x2 rw = *(const u32x2*)(r + col + 4 * j);
;             f32x4 v = (f32x4){bf_lo(rw.x), bf_hi(rw.x), bf_lo(rw.y), bf_hi(rw.y)};
;             float ss = v[0] * v[0] + v[1] * v[1] + v[2] * v[2] + v[3] * v[3];
; #pragma unroll
;             for (int o = 16; o > 0; o >>= 1) ss += __shfl_xor(ss, o);
;             const float rn = rinv_of(ss, 1.0f / 128.0f);
.LBB0_748:
	v_and_b32_e32 v40, 0xfff, v62
	v_cvt_f64_u32_e32 v[40:41], v40
	s_mov_b32 s0, 0x6dc9c883
	v_mul_f64 v[42:43], v[0:1], v[40:41]
	s_mov_b32 s1, 0x3fc45f30
	v_mul_f64 v[44:45], v[42:43], s[0:1]
	v_rndne_f64_e32 v[44:45], v[44:45]
	v_fma_f64 v[42:43], v[42:43], s[0:1], -v[44:45]
	v_mul_f64 v[44:45], v[4:5], v[40:41]
	v_mul_f64 v[48:49], v[44:45], s[0:1]
	v_rndne_f64_e32 v[48:49], v[48:49]
	v_fma_f64 v[44:45], v[44:45], s[0:1], -v[48:49]
	v_cvt_f32_f64_e32 v42, v[42:43]
	v_cvt_f32_f64_e32 v43, v[44:45]
	v_mul_f64 v[44:45], v[8:9], v[40:41]
	v_mul_f64 v[50:51], v[12:13], v[40:41]
	v_mul_f64 v[48:49], v[44:45], s[0:1]
	s_waitcnt lgkmcnt(0)
	v_mul_f64 v[52:53], v[50:51], s[0:1]
	v_rndne_f64_e32 v[48:49], v[48:49]
	v_rndne_f64_e32 v[52:53], v[52:53]
	v_fma_f64 v[44:45], v[44:45], s[0:1], -v[48:49]
	v_fma_f64 v[50:51], v[50:51], s[0:1], -v[52:53]
	v_cvt_f32_f64_e32 v44, v[44:45]
	v_cvt_f32_f64_e32 v45, v[50:51]
	v_lshl_add_u64 v[50:51], s[2:3], 0, v[26:27]
	s_mov_b32 s0, 0x1b500000
	v_add_co_u32_e32 v54, vcc, s0, v50
	v_sin_f32_e32 v46, v42
	s_nop 0
	v_addc_co_u32_e32 v55, vcc, 0, v51, vcc
	global_load_dwordx2 v[56:57], v[54:55], off
	v_readlane_b32 s26, v254, 15
	v_readlane_b32 s27, v254, 16
	v_mbcnt_lo_u32_b32 v216, -1, 0
	v_mbcnt_hi_u32_b32 v216, -1, v216
	v_lshlrev_b32_e32 v216, 3, v216
	v_mov_b32_e32 v217, 0
	s_mov_b64 s[28:29], 0x2000
	v_lshl_add_u64 v[212:213], v[54:55], 0, s[26:27]
	v_lshl_add_u64 v[212:213], v[212:213], 0, v[216:217]
	v_lshl_add_u64 v[214:215], v[212:213], 0, s[28:29]
	global_load_dwordx4 v[208:211], v[212:213], off
	global_load_dwordx4 v[208:211], v[212:213], off offset:1024
	global_load_dwordx4 v[208:211], v[212:213], off offset:2048
	global_load_dwordx4 v[208:211], v[212:213], off offset:3072
	global_load_dwordx4 v[208:211], v[214:215], off offset:-4096
	global_load_dwordx4 v[208:211], v[214:215], off offset:-3072
	global_load_dwordx4 v[208:211], v[214:215], off offset:-2048
	global_load_dwordx4 v[208:211], v[214:215], off offset:-1024
	global_load_dwordx4 v[208:211], v[214:215], off
	v_cos_f32_e32 v42, v42
	v_sin_f32_e32 v47, v43
	v_cos_f32_e32 v43, v43
	v_sin_f32_e32 v48, v44
	v_cos_f32_e32 v44, v44
	v_sin_f32_e32 v49, v45
	v_cos_f32_e32 v45, v45
	s_waitcnt vmcnt(0)
	v_lshlrev_b32_e32 v60, 16, v56
	v_and_b32_e32 v61, 0xffff0000, v56
	v_and_b32_e32 v52, 0xffff0000, v57
	v_pk_mul_f32 v[58:59], v[60:61], v[60:61]
	v_and_b32_e32 v53, s0, v57
	v_lshlrev_b32_e32 v57, 16, v57
	v_mov_b32_e32 v56, v52
	v_pk_mul_f32 v[68:69], v[56:57], v[56:57]
	v_add_f32_e32 v58, v58, v59
	v_add_f32_e32 v58, v69, v58
	v_add_f32_e32 v58, v68, v58
	global_load_dwordx4 v[68:71], v[16:17], off
	ds_bpermute_b32 v59, v64, v58
	v_pk_mov_b32 v[52:53], v[56:57], v[52:53] op_sel:[1,0]
	s_waitcnt lgkmcnt(0)
	v_add_f32_e32 v58, v58, v59
	ds_bpermute_b32 v59, v65, v58
	s_waitcnt lgkmcnt(0)
	v_add_f32_e32 v58, v58, v59
	ds_bpermute_b32 v59, v63, v58
	s_waitcnt lgkmcnt(0)
	v_add_f32_e32 v58, v58, v59
	ds_bpermute_b32 v59, v66, v58
	s_waitcnt lgkmcnt(0)
	v_add_f32_e32 v58, v58, v59
	ds_bpermute_b32 v59, v67, v58
	s_waitcnt lgkmcnt(0)
	v_add_f32_e32 v58, v58, v59
	v_fmamk_f32 v58, v58, 0x3c000000, v189
	v_cmp_gt_f32_e32 vcc, s78, v58
	v_mul_f32_e32 v59, 0x4b800000, v58
	s_nop 0
	v_cndmask_b32_e32 v58, v58, v59, vcc
	v_rsq_f32_e32 v58, v58
	s_nop 0
	v_mul_f32_e32 v59, 0x45800000, v58
	v_cndmask_b32_e32 v58, v58, v59, vcc
	v_pk_mul_f32 v[60:61], v[58:59], v[60:61] op_sel_hi:[0,1]
	v_pk_mul_f32 v[52:53], v[58:59], v[52:53] op_sel_hi:[0,1]
	s_waitcnt vmcnt(0)
	v_pk_mul_f32 v[52:53], v[70:71], v[52:53]
	v_pk_mul_f32 v[56:57], v[68:69], v[60:61]
	ds_bpermute_b32 v60, v63, v56
	ds_bpermute_b32 v61, v63, v57
	ds_bpermute_b32 v58, v63, v52
	ds_bpermute_b32 v59, v63, v53
	s_and_saveexec_b64 s[22:23], s[8:9]
	s_cbranch_execz .LBB0_750
	s_waitcnt lgkmcnt(2)
	v_pk_mul_f32 v[60:61], v[46:47], v[60:61]
	s_waitcnt lgkmcnt(0)
	v_pk_mul_f32 v[58:59], v[48:49], v[58:59]
	v_cndmask_b32_e64 v61, v61, -v61, s[10:11]
	v_cndmask_b32_e64 v60, v60, -v60, s[10:11]
	v_cndmask_b32_e64 v59, v59, -v59, s[10:11]
	v_cndmask_b32_e64 v58, v58, -v58, s[10:11]
	v_pk_fma_f32 v[56:57], v[42:43], v[56:57], v[60:61]
	v_pk_fma_f32 v[52:53], v[44:45], v[52:53], v[58:59]

; #define LAS __attribute__((address_space(3)))
; __device__ __forceinline__ void conv_phase(const int TID, const int BID, PP p, LAS unsigned* ldsw) {
;     const int t = TID, G = gridDim.x;
;     int m = 0; ConvDesc d = conv_desc(p, 0); int base = 0;
;     int total = 0;
;     for (int i = 0; i < 20; ++i) total += conv_desc(p, i).ntiles;
;     int gid = BID;
;     f32x4 a[2][2];
;     bool have = gid < total;
;     if (have) { while (gid >= base + d.ntiles) { base += d.ntiles; ++m; d = conv_desc(p, m); } conv_load(TID, d, gid - base, a); }
.LBB0_1270:
	s_add_u32 s8, s2, 0x2d00000
	s_addc_u32 s9, s3, 0
	s_add_u32 s18, s2, 0x1d00000
	v_and_b32_e32 v18, 64, v195
	s_addc_u32 s19, s3, 0
	v_lshrrev_b32_e32 v16, 4, v195
	v_and_or_b32 v24, v152, 60, v18
	s_add_u32 s20, s2, 0x1500000
	v_ashrrev_i32_e32 v18, 5, v195
	s_addc_u32 s21, s3, 0
	v_and_b32_e32 v19, -4, v18
	v_bfi_b32 v18, -4, v18, v16
	s_add_u32 s22, s2, 0x400000
	v_lshlrev_b32_e32 v25, 1, v18
	v_add_u32_e32 v18, 0x200, v195
	s_addc_u32 s23, s3, 0
	v_ashrrev_i32_e32 v18, 5, v18
	v_bfe_u32 v17, v195, 4, 2
	s_add_u32 s37, s2, 0xb500000
	v_bfi_b32 v16, -4, v18, v16
	v_ashrrev_i32_e32 v27, 2, v195
	s_movk_i32 s24, 0x84
	v_lshl_add_u32 v17, v17, 2, s95
	s_addc_u32 s38, s3, 0
	v_and_b32_e32 v20, -4, v18
	v_lshlrev_b32_e32 v26, 1, v16
	v_and_b32_e32 v16, 3, v195
	v_mul_lo_u32 v18, v27, s24
	s_add_u32 s39, s2, 0x3500000
	v_add_u32_e32 v18, s95, v18
	v_lshlrev_b32_e32 v21, 5, v16
	v_lshlrev_b32_e32 v16, 4, v16
	v_lshl_add_u32 v19, v19, 2, v17
	v_mul_u32_u24_e32 v22, 0x84, v24
	v_lshl_add_u32 v17, v20, 2, v17
	s_addc_u32 s40, s3, 0
	v_add_u32_e32 v28, v19, v22
	v_add_u32_e32 v29, v17, v22
	v_add_u32_e32 v30, v18, v21
	v_lshlrev_b32_e32 v160, 1, v16
	s_mov_b32 s41, s92
	s_mov_b32 s32, 0
	s_waitcnt vmcnt(0)
	s_branch .LBB0_1273

; __device__ __forceinline__ unsigned cvt_pk_bf16(float lo, float hi) { unsigned r; asm volatile("v_cvt_pk_bf16_f32 %0, %1, %2" : "=v"(r) : "v"(lo), "v"(hi)); return r; }
; __device__ __forceinline__ void conv_load(const int TID, const ConvDesc& d, int tile, f32x4 (&a)[2][2]) {
;     ...
;         if (d.ks) { a[i][0] *= d.ks[k]; a[i][1] *= d.ks[k + 1]; }
; __device__ __forceinline__ void conv_phase(const int TID, const int BID, PP p, LAS unsigned* ldsw) {
;     ...
;     while (have) {
;         const ConvDesc cd = d; const int ctile = gid - base;
;         __syncthreads();
; #pragma unroll
;         for (int i = 0; i < 2; ++i) {
;             const int u = t + 512 * i, nq = (u & 15) + 16 * ((u >> 6) & 1), kp = ((u >> 4) & 3) + 4 * (u >> 7);
; #pragma unroll
;             for (int e = 0; e < 4; ++e) ldsw[(4 * nq + e) * 33 + kp] = cvt_pk_bf16(a[i][0][e], a[i][1][e]);
;         }
.LBB0_1273:
	s_waitcnt lgkmcnt(0)
	s_barrier
	s_waitcnt vmcnt(2)
	s_cmp_eq_u32 s32, 0
	s_cbranch_scc1 .Lconv_noscale
	v_pk_mul_f32 v[2:3], v[2:3], v[242:243] op_sel_hi:[1,0]
	v_pk_mul_f32 v[0:1], v[0:1], v[242:243] op_sel_hi:[1,0]
	v_pk_mul_f32 v[6:7], v[6:7], v[242:243] op_sel:[0,1]
	v_pk_mul_f32 v[4:5], v[4:5], v[242:243] op_sel:[0,1]
	v_pk_mul_f32 v[10:11], v[10:11], v[244:245] op_sel_hi:[1,0]
	v_pk_mul_f32 v[8:9], v[8:9], v[244:245] op_sel_hi:[1,0]
	v_pk_mul_f32 v[14:15], v[14:15], v[244:245] op_sel:[0,1]
	v_pk_mul_f32 v[12:13], v[12:13], v[244:245] op_sel:[0,1]
.Lconv_noscale:
	v_cvt_pk_bf16_f32 v16, v0, v4
	ds_write_b32 v28, v16
	v_cvt_pk_bf16_f32 v16, v1, v5
	ds_write_b32 v28, v16 offset:132
	v_cvt_pk_bf16_f32 v16, v2, v6
	ds_write_b32 v28, v16 offset:264
	v_cvt_pk_bf16_f32 v16, v3, v7
	s_add_i32 s42, s41, s70
	ds_write_b32 v28, v16 offset:396
	v_cvt_pk_bf16_f32 v16, v8, v12
	s_cmpk_gt_i32 s42, 0x4d3f
	ds_write_b32 v29, v16
	v_cvt_pk_bf16_f32 v16, v9, v13
	s_cselect_b64 s[24:25], -1, 0
	ds_write_b32 v29, v16 offset:132
	v_cvt_pk_bf16_f32 v16, v10, v14
	s_and_b64 vcc, exec, s[24:25]
	ds_write_b32 v29, v16 offset:264
	v_cvt_pk_bf16_f32 v16, v11, v15
	ds_write_b32 v29, v16 offset:396
	s_cbranch_vccnz .LBB0_1271
	s_add_i32 s43, s34, s0
	s_cmp_lt_i32 s42, s43
	s_cbranch_scc1 .LBB0_1301
	s_lshl_b32 s4, s36, 11
	s_add_i32 s28, s4, 0xffffa800
	s_add_i32 s30, s36, 1
	s_cmp_gt_i32 s36, 6
	s_mov_b64 s[34:35], -1
	s_cbranch_scc0 .LBB0_1295

; __device__ __forceinline__ void conv_load(const int TID, const ConvDesc& d, int tile, f32x4 (&a)[2][2]) {
;     ...
;     for (int i = 0; i < 2; ++i) {
;         const int u = t + 512 * i, nq = (u & 15) + 16 * ((u >> 6) & 1), kp = ((u >> 4) & 3) + 4 * (u >> 7);
;         const int k = kb * 64 + 2 * kp, n = nb * 128 + 4 * nq;
;         if (n < d.N) { a[i][0] = *(const f32x4*)(d.src + (size_t)k * d.N + n); a[i][1] = *(const f32x4*)(d.src + (size_t)(k + 1) * d.N + n); }
;         else { a[i][0] = (f32x4){0.f, 0.f, 0.f, 0.f}; a[i][1] = (f32x4){0.f, 0.f, 0.f, 0.f}; }
;         if (d.ks) { a[i][0] *= d.ks[k]; a[i][1] *= d.ks[k + 1]; }
.LBB0_1305:
	s_or_b64 exec, exec, s[28:29]
	s_cmp_lg_u64 s[16:17], 0
	s_cselect_b64 s[28:29], -1, 0
	s_cselect_b32 s32, 1, 0
	s_cmp_eq_u64 s[16:17], 0
	s_cbranch_scc1 .LBB0_1307
	v_ashrrev_i32_e32 v9, 31, v8
	v_lshl_add_u64 v[240:241], v[8:9], 2, s[16:17]
	global_load_dwordx2 v[242:243], v[240:241], off

; __device__ __forceinline__ void conv_load(const int TID, const ConvDesc& d, int tile, f32x4 (&a)[2][2]) {
;     ...
;     for (int i = 0; i < 2; ++i) {
;         const int u = t + 512 * i, nq = (u & 15) + 16 * ((u >> 6) & 1), kp = ((u >> 4) & 3) + 4 * (u >> 7);
;         const int k = kb * 64 + 2 * kp, n = nb * 128 + 4 * nq;
;         if (n < d.N) { a[i][0] = *(const f32x4*)(d.src + (size_t)k * d.N + n); a[i][1] = *(const f32x4*)(d.src + (size_t)(k + 1) * d.N + n); }
;         else { a[i][0] = (f32x4){0.f, 0.f, 0.f, 0.f}; a[i][1] = (f32x4){0.f, 0.f, 0.f, 0.f}; }
;         if (d.ks) { a[i][0] *= d.ks[k]; a[i][1] *= d.ks[k + 1]; }
;     }
.LBB0_1311:
	s_or_b64 exec, exec, s[30:31]
	s_andn2_b64 vcc, exec, s[28:29]
	s_cbranch_vccnz .LBB0_1313
	v_ashrrev_i32_e32 v19, 31, v18
	v_lshl_add_u64 v[240:241], v[18:19], 2, s[16:17]
	global_load_dwordx2 v[244:245], v[240:241], off
	s_branch .LBB0_1272
